# diff-attention fast loop: kh loop unrolled, fragment addresses hoisted per tile, LDS reads preloaded, exp/cvt interleaved with MFMAs, merged waits (on top of the GQA version)
# speedup vs baseline: 1.0175x; 1.0075x over previous
; #define MFMA32(a, b, c) __builtin_amdgcn_mfma_f32_32x32x16_bf16((a), (b), (c), 0, 0, 0)
; DI float fadd1(float a, float b) { float r; asm("v_add_f32 %0, %1, %2" : "=v"(r) : "v"(a), "v"(b)); return r; }
; template <int NKS>
; DI void attn_tile(const Params& p, int layer, int seq, int slot, int qt, char* smem, bool wr = true) {
;     ...
; #pragma unroll 1
;       for (int kh = 0; kh < 2; ++kh) {
;       const u16* sK = (const u16*)(smem + (kt & 1) * 32768 + kh * 8192);
;       const u16* sV = (const u16*)(smem + (kt & 1) * 32768 + 16384 + kh * 8192);
;       auto kb_body = [&](int kb) {
;         bf16x8 kf[NKS];
; #pragma unroll
;         for (int ks = 0; ks < NKS; ++ks) kf[ks] = *(const bf16x8*)(sK + swz(32 * kb + r, 2 * (ks0 + ks) + h));
;         bf16x8 pk[2][2];
; #pragma unroll
;         for (int qb = 0; qb < 2; ++qb) {
;           f32x16 st;
; #pragma unroll
;           for (int i = 0; i < 16; ++i) st[i] = SUB ? ncb[qb] : 0.f;
; #pragma unroll
;           for (int ks = 0; ks < NKS; ++ks) st = MFMA32(kf[ks], qf[qb][ks], st);
;           if constexpr (SUB) {
;             float ls = 0.f;
; #pragma unroll
;             for (int i = 0; i < 16; ++i) { float e = __builtin_amdgcn_exp2f(st[i]); st[i] = e; ls = fadd1(ls, e); }
;             lsum[qb] += ls;
;             pk[qb][0] = pack8(st, 0); pk[qb][1] = pack8(st, 1);
;           } else {
; #pragma unroll
;             for (int i = 0; i < 16; ++i) st[i] = __builtin_amdgcn_exp2f(st[i]);
;             pk[qb][0] = pack8(st, 0); pk[qb][1] = pack8(st, 1);
;             ls4[qb] = __builtin_amdgcn_mfma_f32_16x16x32_bf16(selA, pk[qb][0], ls4[qb], 0, 0, 0);
;             ls4[qb] = __builtin_amdgcn_mfma_f32_16x16x32_bf16(selA, pk[qb][1], ls4[qb], 0, 0, 0);
;           }
;         }
; #pragma unroll
;         for (int eb = 0; eb < 2; ++eb)
; #pragma unroll
;           for (int s2 = 0; s2 < 2; ++s2) {
;             bf16x8 vf = *(const bf16x8*)(sV + swz(32 * eb + r, 4 * kb + 2 * s2 + h));
; #pragma unroll
;             for (int qb = 0; qb < 2; ++qb) O[qb][eb] = MFMA32(vf, pk[qb][s2], O[qb][eb]);
;           }
;       };
.LBB0_674:
	v_add3_u32 v128, s14, v172, v178
	v_add3_u32 v130, s14, v173, v178
	v_add3_u32 v131, s14, v174, v178
	v_add3_u32 v188, s14, v175, v178
	v_add3_u32 v189, s14, v176, v178
	v_add3_u32 v190, s14, v177, v178
	ds_read_b128 v[180:183], v128
	ds_read_b128 v[184:187], v130
	ds_read_b128 v[204:207], v128 offset:4096
	ds_read_b128 v[208:211], v130 offset:4096
	ds_read_b128 v[212:215], v131 offset:16384
	ds_read_b128 v[216:219], v131 offset:20480
	ds_read_b128 v[220:223], v188 offset:16384
	ds_read_b128 v[224:227], v188 offset:20480
	ds_read_b128 v[228:231], v189 offset:16384
	s_waitcnt lgkmcnt(7)
	v_mfma_f32_32x32x16_bf16 v[112:127], v[180:183], v[132:135], 0
	v_mfma_f32_32x32x16_bf16 v[112:127], v[184:187], v[136:139], v[112:127]
	v_mfma_f32_32x32x16_bf16 v[96:111], v[180:183], v[140:143], 0
	v_mfma_f32_32x32x16_bf16 v[96:111], v[184:187], v[144:147], v[96:111]
	ds_read_b128 v[180:183], v189 offset:20480
	ds_read_b128 v[184:187], v190 offset:16384
	s_waitcnt lgkmcnt(7)
	v_mfma_f32_32x32x16_bf16 v[64:79], v[204:207], v[132:135], 0
	v_mfma_f32_32x32x16_bf16 v[64:79], v[208:211], v[136:139], v[64:79]
	s_nop 4
	v_exp_f32_e32 v112, v112
	v_exp_f32_e32 v113, v113
	v_exp_f32_e32 v114, v114
	v_exp_f32_e32 v115, v115
	v_cvt_pk_bf16_f32 v112, v112, v113
	v_cvt_pk_bf16_f32 v113, v114, v115
	v_mfma_f32_32x32x16_bf16 v[80:95], v[204:207], v[140:143], 0
	ds_read_b128 v[204:207], v190 offset:20480
	v_exp_f32_e32 v116, v116
	v_exp_f32_e32 v117, v117
	v_exp_f32_e32 v118, v118
	v_exp_f32_e32 v119, v119
	v_cvt_pk_bf16_f32 v114, v116, v117
	v_cvt_pk_bf16_f32 v115, v118, v119
	v_mfma_f32_32x32x16_bf16 v[80:95], v[208:211], v[144:147], v[80:95]
	v_exp_f32_e32 v120, v120
	v_exp_f32_e32 v121, v121
	v_exp_f32_e32 v122, v122
	v_exp_f32_e32 v123, v123
	v_cvt_pk_bf16_f32 v116, v120, v121
	v_cvt_pk_bf16_f32 v117, v122, v123
	s_waitcnt lgkmcnt(6)
	v_mfma_f32_32x32x16_bf16 v[48:63], v[212:215], v[112:115], v[48:63]
	v_exp_f32_e32 v124, v124
	v_exp_f32_e32 v125, v125
	v_exp_f32_e32 v126, v126
	v_exp_f32_e32 v127, v127
	v_cvt_pk_bf16_f32 v118, v124, v125
	v_cvt_pk_bf16_f32 v119, v126, v127
	v_mfma_f32_32x32x16_bf16 v[32:47], v[216:219], v[112:115], v[32:47]
	v_exp_f32_e32 v96, v96
	v_exp_f32_e32 v97, v97
	v_exp_f32_e32 v98, v98
	v_exp_f32_e32 v99, v99
	v_cvt_pk_bf16_f32 v96, v96, v97
	v_cvt_pk_bf16_f32 v97, v98, v99
	v_mfma_f32_16x16x32_bf16 v[148:151], v[156:159], v[112:115], v[148:151]
	s_waitcnt lgkmcnt(4)
	v_mfma_f32_32x32x16_bf16 v[48:63], v[220:223], v[116:119], v[48:63]
	v_exp_f32_e32 v100, v100
	v_exp_f32_e32 v101, v101
	v_exp_f32_e32 v102, v102
	v_exp_f32_e32 v103, v103
	v_cvt_pk_bf16_f32 v98, v100, v101
	v_cvt_pk_bf16_f32 v99, v102, v103
	v_mfma_f32_32x32x16_bf16 v[32:47], v[224:227], v[116:119], v[32:47]
	v_mfma_f32_16x16x32_bf16 v[148:151], v[156:159], v[116:119], v[148:151]
	v_exp_f32_e32 v104, v104
	v_exp_f32_e32 v105, v105
	v_exp_f32_e32 v106, v106
	v_exp_f32_e32 v107, v107
	v_cvt_pk_bf16_f32 v100, v104, v105
	v_cvt_pk_bf16_f32 v101, v106, v107
	v_mfma_f32_32x32x16_bf16 v[16:31], v[212:215], v[96:99], v[16:31]
	v_exp_f32_e32 v108, v108
	v_exp_f32_e32 v109, v109
	v_exp_f32_e32 v110, v110
	v_exp_f32_e32 v111, v111
	v_cvt_pk_bf16_f32 v102, v108, v109
	v_cvt_pk_bf16_f32 v103, v110, v111
	v_mfma_f32_32x32x16_bf16 v[0:15], v[216:219], v[96:99], v[0:15]
	v_mfma_f32_16x16x32_bf16 v[152:155], v[156:159], v[96:99], v[152:155]
	v_exp_f32_e32 v64, v64
	v_exp_f32_e32 v65, v65
	v_exp_f32_e32 v66, v66
	v_exp_f32_e32 v67, v67
	v_cvt_pk_bf16_f32 v64, v64, v65
	v_cvt_pk_bf16_f32 v65, v66, v67
	v_mfma_f32_32x32x16_bf16 v[16:31], v[220:223], v[100:103], v[16:31]
	v_mfma_f32_32x32x16_bf16 v[0:15], v[224:227], v[100:103], v[0:15]
	v_exp_f32_e32 v68, v68
	v_exp_f32_e32 v69, v69
	v_exp_f32_e32 v70, v70
	v_exp_f32_e32 v71, v71
	v_cvt_pk_bf16_f32 v66, v68, v69
	v_cvt_pk_bf16_f32 v67, v70, v71
	v_mfma_f32_16x16x32_bf16 v[152:155], v[156:159], v[100:103], v[152:155]
	s_waitcnt lgkmcnt(2)
	v_mfma_f32_32x32x16_bf16 v[48:63], v[228:231], v[64:67], v[48:63]
	v_exp_f32_e32 v72, v72
	v_exp_f32_e32 v73, v73
	v_exp_f32_e32 v74, v74
	v_exp_f32_e32 v75, v75
	v_cvt_pk_bf16_f32 v68, v72, v73
	v_cvt_pk_bf16_f32 v69, v74, v75
	v_mfma_f32_32x32x16_bf16 v[32:47], v[180:183], v[64:67], v[32:47]
	v_mfma_f32_16x16x32_bf16 v[148:151], v[156:159], v[64:67], v[148:151]
	v_exp_f32_e32 v76, v76
	v_exp_f32_e32 v77, v77
	v_exp_f32_e32 v78, v78
	v_exp_f32_e32 v79, v79
	v_cvt_pk_bf16_f32 v70, v76, v77
	v_cvt_pk_bf16_f32 v71, v78, v79
	s_waitcnt lgkmcnt(0)
	s_nop 0
	v_mfma_f32_32x32x16_bf16 v[48:63], v[184:187], v[68:71], v[48:63]
	v_exp_f32_e32 v80, v80
	v_exp_f32_e32 v81, v81
	v_exp_f32_e32 v82, v82
	v_exp_f32_e32 v83, v83
	v_cvt_pk_bf16_f32 v80, v80, v81
	v_cvt_pk_bf16_f32 v81, v82, v83
	v_mfma_f32_32x32x16_bf16 v[32:47], v[204:207], v[68:71], v[32:47]
	v_mfma_f32_16x16x32_bf16 v[148:151], v[156:159], v[68:71], v[148:151]
	v_exp_f32_e32 v84, v84
	v_exp_f32_e32 v85, v85
	v_exp_f32_e32 v86, v86
	v_exp_f32_e32 v87, v87
	v_cvt_pk_bf16_f32 v82, v84, v85
	v_cvt_pk_bf16_f32 v83, v86, v87
	v_exp_f32_e32 v88, v88
	v_exp_f32_e32 v89, v89
	v_exp_f32_e32 v90, v90
	v_exp_f32_e32 v91, v91
	v_cvt_pk_bf16_f32 v84, v88, v89
	v_cvt_pk_bf16_f32 v85, v90, v91
	v_mfma_f32_32x32x16_bf16 v[16:31], v[228:231], v[80:83], v[16:31]
	v_exp_f32_e32 v92, v92
	v_exp_f32_e32 v93, v93
	v_exp_f32_e32 v94, v94
	v_exp_f32_e32 v95, v95
	v_cvt_pk_bf16_f32 v86, v92, v93
	v_cvt_pk_bf16_f32 v87, v94, v95
	v_mfma_f32_32x32x16_bf16 v[0:15], v[180:183], v[80:83], v[0:15]
	v_mfma_f32_16x16x32_bf16 v[152:155], v[156:159], v[80:83], v[152:155]
	v_mfma_f32_32x32x16_bf16 v[16:31], v[184:187], v[84:87], v[16:31]
	v_mfma_f32_32x32x16_bf16 v[0:15], v[204:207], v[84:87], v[0:15]
	v_mfma_f32_16x16x32_bf16 v[152:155], v[156:159], v[84:87], v[152:155]
	ds_read_b128 v[180:183], v128 offset:8192
	ds_read_b128 v[184:187], v130 offset:8192
	ds_read_b128 v[204:207], v128 offset:12288
	ds_read_b128 v[208:211], v130 offset:12288
	ds_read_b128 v[212:215], v131 offset:24576
	ds_read_b128 v[216:219], v131 offset:28672
	ds_read_b128 v[220:223], v188 offset:24576
	ds_read_b128 v[224:227], v188 offset:28672
	ds_read_b128 v[228:231], v189 offset:24576
	s_waitcnt lgkmcnt(7)
; #define MFMA32(a, b, c) __builtin_amdgcn_mfma_f32_32x32x16_bf16((a), (b), (c), 0, 0, 0)
; DI float fadd1(float a, float b) { float r; asm("v_add_f32 %0, %1, %2" : "=v"(r) : "v"(a), "v"(b)); return r; }
; template <int NKS>
; DI void attn_tile(const Params& p, int layer, int seq, int slot, int qt, char* smem, bool wr = true) {
;     ...
;       auto kb_body = [&](int kb) {
;         bf16x8 kf[NKS];
; #pragma unroll
;         for (int ks = 0; ks < NKS; ++ks) kf[ks] = *(const bf16x8*)(sK + swz(32 * kb + r, 2 * (ks0 + ks) + h));
;         bf16x8 pk[2][2];
; #pragma unroll
;         for (int qb = 0; qb < 2; ++qb) {
;           f32x16 st;
; #pragma unroll
;           for (int i = 0; i < 16; ++i) st[i] = SUB ? ncb[qb] : 0.f;
; #pragma unroll
;           for (int ks = 0; ks < NKS; ++ks) st = MFMA32(kf[ks], qf[qb][ks], st);
;           if constexpr (SUB) {
;             float ls = 0.f;
; #pragma unroll
;             for (int i = 0; i < 16; ++i) { float e = __builtin_amdgcn_exp2f(st[i]); st[i] = e; ls = fadd1(ls, e); }
;             lsum[qb] += ls;
;             pk[qb][0] = pack8(st, 0); pk[qb][1] = pack8(st, 1);
;           } else {
; #pragma unroll
;             for (int i = 0; i < 16; ++i) st[i] = __builtin_amdgcn_exp2f(st[i]);
;             pk[qb][0] = pack8(st, 0); pk[qb][1] = pack8(st, 1);
;             ls4[qb] = __builtin_amdgcn_mfma_f32_16x16x32_bf16(selA, pk[qb][0], ls4[qb], 0, 0, 0);
;             ls4[qb] = __builtin_amdgcn_mfma_f32_16x16x32_bf16(selA, pk[qb][1], ls4[qb], 0, 0, 0);
;           }
;         }
; #pragma unroll
;         for (int eb = 0; eb < 2; ++eb)
; #pragma unroll
;           for (int s2 = 0; s2 < 2; ++s2) {
;             bf16x8 vf = *(const bf16x8*)(sV + swz(32 * eb + r, 4 * kb + 2 * s2 + h));
; #pragma unroll
;             for (int qb = 0; qb < 2; ++qb) O[qb][eb] = MFMA32(vf, pk[qb][s2], O[qb][eb]);
;           }
;       };
;       if constexpr (SUB) {
; #pragma unroll 1
;         for (int kb = 0; kb < 2; ++kb) kb_body(kb);
;       } else {
;         kb_body(0); kb_body(1);
;       }
;       }
;     }
	v_mfma_f32_32x32x16_bf16 v[112:127], v[180:183], v[132:135], 0
	v_mfma_f32_32x32x16_bf16 v[112:127], v[184:187], v[136:139], v[112:127]
	v_mfma_f32_32x32x16_bf16 v[96:111], v[180:183], v[140:143], 0
	v_mfma_f32_32x32x16_bf16 v[96:111], v[184:187], v[144:147], v[96:111]
	ds_read_b128 v[180:183], v189 offset:28672
	ds_read_b128 v[184:187], v190 offset:24576
	s_waitcnt lgkmcnt(7)
	v_mfma_f32_32x32x16_bf16 v[64:79], v[204:207], v[132:135], 0
	v_mfma_f32_32x32x16_bf16 v[64:79], v[208:211], v[136:139], v[64:79]
	s_nop 4
	v_exp_f32_e32 v112, v112
	v_exp_f32_e32 v113, v113
	v_exp_f32_e32 v114, v114
	v_exp_f32_e32 v115, v115
	v_cvt_pk_bf16_f32 v112, v112, v113
	v_cvt_pk_bf16_f32 v113, v114, v115
	v_mfma_f32_32x32x16_bf16 v[80:95], v[204:207], v[140:143], 0
	ds_read_b128 v[204:207], v190 offset:28672
	v_exp_f32_e32 v116, v116
	v_exp_f32_e32 v117, v117
	v_exp_f32_e32 v118, v118
	v_exp_f32_e32 v119, v119
	v_cvt_pk_bf16_f32 v114, v116, v117
	v_cvt_pk_bf16_f32 v115, v118, v119
	v_mfma_f32_32x32x16_bf16 v[80:95], v[208:211], v[144:147], v[80:95]
	v_exp_f32_e32 v120, v120
	v_exp_f32_e32 v121, v121
	v_exp_f32_e32 v122, v122
	v_exp_f32_e32 v123, v123
	v_cvt_pk_bf16_f32 v116, v120, v121
	v_cvt_pk_bf16_f32 v117, v122, v123
	s_waitcnt lgkmcnt(6)
	v_mfma_f32_32x32x16_bf16 v[48:63], v[212:215], v[112:115], v[48:63]
	v_exp_f32_e32 v124, v124
	v_exp_f32_e32 v125, v125
	v_exp_f32_e32 v126, v126
	v_exp_f32_e32 v127, v127
	v_cvt_pk_bf16_f32 v118, v124, v125
	v_cvt_pk_bf16_f32 v119, v126, v127
	v_mfma_f32_32x32x16_bf16 v[32:47], v[216:219], v[112:115], v[32:47]
	v_exp_f32_e32 v96, v96
	v_exp_f32_e32 v97, v97
	v_exp_f32_e32 v98, v98
	v_exp_f32_e32 v99, v99
	v_cvt_pk_bf16_f32 v96, v96, v97
	v_cvt_pk_bf16_f32 v97, v98, v99
	v_mfma_f32_16x16x32_bf16 v[148:151], v[156:159], v[112:115], v[148:151]
	s_waitcnt lgkmcnt(4)
	v_mfma_f32_32x32x16_bf16 v[48:63], v[220:223], v[116:119], v[48:63]
	v_exp_f32_e32 v100, v100
	v_exp_f32_e32 v101, v101
	v_exp_f32_e32 v102, v102
	v_exp_f32_e32 v103, v103
	v_cvt_pk_bf16_f32 v98, v100, v101
	v_cvt_pk_bf16_f32 v99, v102, v103
	v_mfma_f32_32x32x16_bf16 v[32:47], v[224:227], v[116:119], v[32:47]
	v_mfma_f32_16x16x32_bf16 v[148:151], v[156:159], v[116:119], v[148:151]
	v_exp_f32_e32 v104, v104
	v_exp_f32_e32 v105, v105
	v_exp_f32_e32 v106, v106
	v_exp_f32_e32 v107, v107
	v_cvt_pk_bf16_f32 v100, v104, v105
	v_cvt_pk_bf16_f32 v101, v106, v107
	v_mfma_f32_32x32x16_bf16 v[16:31], v[212:215], v[96:99], v[16:31]
	v_exp_f32_e32 v108, v108
	v_exp_f32_e32 v109, v109
	v_exp_f32_e32 v110, v110
	v_exp_f32_e32 v111, v111
	v_cvt_pk_bf16_f32 v102, v108, v109
	v_cvt_pk_bf16_f32 v103, v110, v111
	v_mfma_f32_32x32x16_bf16 v[0:15], v[216:219], v[96:99], v[0:15]
	v_mfma_f32_16x16x32_bf16 v[152:155], v[156:159], v[96:99], v[152:155]
	v_exp_f32_e32 v64, v64
	v_exp_f32_e32 v65, v65
	v_exp_f32_e32 v66, v66
	v_exp_f32_e32 v67, v67
	v_cvt_pk_bf16_f32 v64, v64, v65
	v_cvt_pk_bf16_f32 v65, v66, v67
	v_mfma_f32_32x32x16_bf16 v[16:31], v[220:223], v[100:103], v[16:31]
	v_mfma_f32_32x32x16_bf16 v[0:15], v[224:227], v[100:103], v[0:15]
	v_exp_f32_e32 v68, v68
	v_exp_f32_e32 v69, v69
	v_exp_f32_e32 v70, v70
	v_exp_f32_e32 v71, v71
	v_cvt_pk_bf16_f32 v66, v68, v69
	v_cvt_pk_bf16_f32 v67, v70, v71
	v_mfma_f32_16x16x32_bf16 v[152:155], v[156:159], v[100:103], v[152:155]
	s_waitcnt lgkmcnt(2)
	v_mfma_f32_32x32x16_bf16 v[48:63], v[228:231], v[64:67], v[48:63]
	v_exp_f32_e32 v72, v72
	v_exp_f32_e32 v73, v73
	v_exp_f32_e32 v74, v74
	v_exp_f32_e32 v75, v75
	v_cvt_pk_bf16_f32 v68, v72, v73
	v_cvt_pk_bf16_f32 v69, v74, v75
	v_mfma_f32_32x32x16_bf16 v[32:47], v[180:183], v[64:67], v[32:47]
	v_mfma_f32_16x16x32_bf16 v[148:151], v[156:159], v[64:67], v[148:151]
	v_exp_f32_e32 v76, v76
	v_exp_f32_e32 v77, v77
	v_exp_f32_e32 v78, v78
	v_exp_f32_e32 v79, v79
	v_cvt_pk_bf16_f32 v70, v76, v77
	v_cvt_pk_bf16_f32 v71, v78, v79
	s_waitcnt lgkmcnt(0)
	s_nop 0
	v_mfma_f32_32x32x16_bf16 v[48:63], v[184:187], v[68:71], v[48:63]
	v_exp_f32_e32 v80, v80
	v_exp_f32_e32 v81, v81
	v_exp_f32_e32 v82, v82
	v_exp_f32_e32 v83, v83
	v_cvt_pk_bf16_f32 v80, v80, v81
	v_cvt_pk_bf16_f32 v81, v82, v83
	v_mfma_f32_32x32x16_bf16 v[32:47], v[204:207], v[68:71], v[32:47]
	v_mfma_f32_16x16x32_bf16 v[148:151], v[156:159], v[68:71], v[148:151]
	v_exp_f32_e32 v84, v84
	v_exp_f32_e32 v85, v85
	v_exp_f32_e32 v86, v86
	v_exp_f32_e32 v87, v87
	v_cvt_pk_bf16_f32 v82, v84, v85
	v_cvt_pk_bf16_f32 v83, v86, v87
	v_exp_f32_e32 v88, v88
	v_exp_f32_e32 v89, v89
	v_exp_f32_e32 v90, v90
	v_exp_f32_e32 v91, v91
	v_cvt_pk_bf16_f32 v84, v88, v89
	v_cvt_pk_bf16_f32 v85, v90, v91
	v_mfma_f32_32x32x16_bf16 v[16:31], v[228:231], v[80:83], v[16:31]
	v_exp_f32_e32 v92, v92
	v_exp_f32_e32 v93, v93
	v_exp_f32_e32 v94, v94
	v_exp_f32_e32 v95, v95
	v_cvt_pk_bf16_f32 v86, v92, v93
	v_cvt_pk_bf16_f32 v87, v94, v95
	v_mfma_f32_32x32x16_bf16 v[0:15], v[180:183], v[80:83], v[0:15]
	v_mfma_f32_16x16x32_bf16 v[152:155], v[156:159], v[80:83], v[152:155]
	v_mfma_f32_32x32x16_bf16 v[16:31], v[184:187], v[84:87], v[16:31]
	v_mfma_f32_32x32x16_bf16 v[0:15], v[204:207], v[84:87], v[0:15]
	v_mfma_f32_16x16x32_bf16 v[152:155], v[156:159], v[84:87], v[152:155]
	s_cmp_eq_u32 s36, s31
	s_cbranch_scc1 .LBB0_677
	s_mov_b32 s37, s36
	s_branch .LBB0_671

; #define MFMA32(a, b, c) __builtin_amdgcn_mfma_f32_32x32x16_bf16((a), (b), (c), 0, 0, 0)
; DI float fadd1(float a, float b) { float r; asm("v_add_f32 %0, %1, %2" : "=v"(r) : "v"(a), "v"(b)); return r; }
; template <int NKS>
; DI void attn_tile(const Params& p, int layer, int seq, int slot, int qt, char* smem, bool wr = true) {
;     ...
; #pragma unroll 1
;       for (int kh = 0; kh < 2; ++kh) {
;       const u16* sK = (const u16*)(smem + (kt & 1) * 32768 + kh * 8192);
;       const u16* sV = (const u16*)(smem + (kt & 1) * 32768 + 16384 + kh * 8192);
;       auto kb_body = [&](int kb) {
;         bf16x8 kf[NKS];
; #pragma unroll
;         for (int ks = 0; ks < NKS; ++ks) kf[ks] = *(const bf16x8*)(sK + swz(32 * kb + r, 2 * (ks0 + ks) + h));
;         bf16x8 pk[2][2];
; #pragma unroll
;         for (int qb = 0; qb < 2; ++qb) {
;           f32x16 st;
; #pragma unroll
;           for (int i = 0; i < 16; ++i) st[i] = SUB ? ncb[qb] : 0.f;
; #pragma unroll
;           for (int ks = 0; ks < NKS; ++ks) st = MFMA32(kf[ks], qf[qb][ks], st);
;           if constexpr (SUB) {
;             float ls = 0.f;
; #pragma unroll
;             for (int i = 0; i < 16; ++i) { float e = __builtin_amdgcn_exp2f(st[i]); st[i] = e; ls = fadd1(ls, e); }
;             lsum[qb] += ls;
;             pk[qb][0] = pack8(st, 0); pk[qb][1] = pack8(st, 1);
;           } else {
; #pragma unroll
;             for (int i = 0; i < 16; ++i) st[i] = __builtin_amdgcn_exp2f(st[i]);
;             pk[qb][0] = pack8(st, 0); pk[qb][1] = pack8(st, 1);
;             ls4[qb] = __builtin_amdgcn_mfma_f32_16x16x32_bf16(selA, pk[qb][0], ls4[qb], 0, 0, 0);
;             ls4[qb] = __builtin_amdgcn_mfma_f32_16x16x32_bf16(selA, pk[qb][1], ls4[qb], 0, 0, 0);
;           }
;         }
; #pragma unroll
;         for (int eb = 0; eb < 2; ++eb)
; #pragma unroll
;           for (int s2 = 0; s2 < 2; ++s2) {
;             bf16x8 vf = *(const bf16x8*)(sV + swz(32 * eb + r, 4 * kb + 2 * s2 + h));
; #pragma unroll
;             for (int qb = 0; qb < 2; ++qb) O[qb][eb] = MFMA32(vf, pk[qb][s2], O[qb][eb]);
;           }
;       };
.LBB0_1417:
	v_add3_u32 v128, s14, v173, v179
	v_add3_u32 v130, s14, v174, v179
	v_add3_u32 v131, s14, v175, v179
	v_add3_u32 v188, s14, v176, v179
	v_add3_u32 v189, s14, v177, v179
	v_add3_u32 v190, s14, v178, v179
	ds_read_b128 v[180:183], v128
	ds_read_b128 v[184:187], v130
	ds_read_b128 v[204:207], v128 offset:4096
	ds_read_b128 v[208:211], v130 offset:4096
	ds_read_b128 v[212:215], v131 offset:16384
	ds_read_b128 v[216:219], v131 offset:20480
	ds_read_b128 v[220:223], v188 offset:16384
	ds_read_b128 v[224:227], v188 offset:20480
	ds_read_b128 v[228:231], v189 offset:16384
	s_waitcnt lgkmcnt(7)
	v_mfma_f32_32x32x16_bf16 v[112:127], v[180:183], v[132:135], 0
	v_mfma_f32_32x32x16_bf16 v[112:127], v[184:187], v[136:139], v[112:127]
	v_mfma_f32_32x32x16_bf16 v[96:111], v[180:183], v[140:143], 0
	v_mfma_f32_32x32x16_bf16 v[96:111], v[184:187], v[144:147], v[96:111]
	ds_read_b128 v[180:183], v189 offset:20480
	ds_read_b128 v[184:187], v190 offset:16384
	s_waitcnt lgkmcnt(7)
	v_mfma_f32_32x32x16_bf16 v[64:79], v[204:207], v[132:135], 0
	v_mfma_f32_32x32x16_bf16 v[64:79], v[208:211], v[136:139], v[64:79]
	s_nop 4
	v_exp_f32_e32 v112, v112
	v_exp_f32_e32 v113, v113
	v_exp_f32_e32 v114, v114
	v_exp_f32_e32 v115, v115
	v_cvt_pk_bf16_f32 v112, v112, v113
	v_cvt_pk_bf16_f32 v113, v114, v115
	v_mfma_f32_32x32x16_bf16 v[80:95], v[204:207], v[140:143], 0
	ds_read_b128 v[204:207], v190 offset:20480
	v_exp_f32_e32 v116, v116
	v_exp_f32_e32 v117, v117
	v_exp_f32_e32 v118, v118
	v_exp_f32_e32 v119, v119
	v_cvt_pk_bf16_f32 v114, v116, v117
	v_cvt_pk_bf16_f32 v115, v118, v119
	v_mfma_f32_32x32x16_bf16 v[80:95], v[208:211], v[144:147], v[80:95]
	v_exp_f32_e32 v120, v120
	v_exp_f32_e32 v121, v121
	v_exp_f32_e32 v122, v122
	v_exp_f32_e32 v123, v123
	v_cvt_pk_bf16_f32 v116, v120, v121
	v_cvt_pk_bf16_f32 v117, v122, v123
	s_waitcnt lgkmcnt(6)
	v_mfma_f32_32x32x16_bf16 v[48:63], v[212:215], v[112:115], v[48:63]
	v_exp_f32_e32 v124, v124
	v_exp_f32_e32 v125, v125
	v_exp_f32_e32 v126, v126
	v_exp_f32_e32 v127, v127
	v_cvt_pk_bf16_f32 v118, v124, v125
	v_cvt_pk_bf16_f32 v119, v126, v127
	v_mfma_f32_32x32x16_bf16 v[32:47], v[216:219], v[112:115], v[32:47]
	v_exp_f32_e32 v96, v96
	v_exp_f32_e32 v97, v97
	v_exp_f32_e32 v98, v98
	v_exp_f32_e32 v99, v99
	v_cvt_pk_bf16_f32 v96, v96, v97
	v_cvt_pk_bf16_f32 v97, v98, v99
	v_mfma_f32_16x16x32_bf16 v[148:151], v[156:159], v[112:115], v[148:151]
	s_waitcnt lgkmcnt(4)
	v_mfma_f32_32x32x16_bf16 v[48:63], v[220:223], v[116:119], v[48:63]
	v_exp_f32_e32 v100, v100
	v_exp_f32_e32 v101, v101
	v_exp_f32_e32 v102, v102
	v_exp_f32_e32 v103, v103
	v_cvt_pk_bf16_f32 v98, v100, v101
	v_cvt_pk_bf16_f32 v99, v102, v103
	v_mfma_f32_32x32x16_bf16 v[32:47], v[224:227], v[116:119], v[32:47]
	v_mfma_f32_16x16x32_bf16 v[148:151], v[156:159], v[116:119], v[148:151]
	v_exp_f32_e32 v104, v104
	v_exp_f32_e32 v105, v105
	v_exp_f32_e32 v106, v106
	v_exp_f32_e32 v107, v107
	v_cvt_pk_bf16_f32 v100, v104, v105
	v_cvt_pk_bf16_f32 v101, v106, v107
	v_mfma_f32_32x32x16_bf16 v[16:31], v[212:215], v[96:99], v[16:31]
	v_exp_f32_e32 v108, v108
	v_exp_f32_e32 v109, v109
	v_exp_f32_e32 v110, v110
	v_exp_f32_e32 v111, v111
	v_cvt_pk_bf16_f32 v102, v108, v109
	v_cvt_pk_bf16_f32 v103, v110, v111
	v_mfma_f32_32x32x16_bf16 v[0:15], v[216:219], v[96:99], v[0:15]
	v_mfma_f32_16x16x32_bf16 v[152:155], v[156:159], v[96:99], v[152:155]
	v_exp_f32_e32 v64, v64
	v_exp_f32_e32 v65, v65
	v_exp_f32_e32 v66, v66
	v_exp_f32_e32 v67, v67
	v_cvt_pk_bf16_f32 v64, v64, v65
	v_cvt_pk_bf16_f32 v65, v66, v67
	v_mfma_f32_32x32x16_bf16 v[16:31], v[220:223], v[100:103], v[16:31]
	v_mfma_f32_32x32x16_bf16 v[0:15], v[224:227], v[100:103], v[0:15]
	v_exp_f32_e32 v68, v68
	v_exp_f32_e32 v69, v69
	v_exp_f32_e32 v70, v70
	v_exp_f32_e32 v71, v71
	v_cvt_pk_bf16_f32 v66, v68, v69
	v_cvt_pk_bf16_f32 v67, v70, v71
	v_mfma_f32_16x16x32_bf16 v[152:155], v[156:159], v[100:103], v[152:155]
	s_waitcnt lgkmcnt(2)
	v_mfma_f32_32x32x16_bf16 v[48:63], v[228:231], v[64:67], v[48:63]
	v_exp_f32_e32 v72, v72
	v_exp_f32_e32 v73, v73
	v_exp_f32_e32 v74, v74
	v_exp_f32_e32 v75, v75
	v_cvt_pk_bf16_f32 v68, v72, v73
	v_cvt_pk_bf16_f32 v69, v74, v75
	v_mfma_f32_32x32x16_bf16 v[32:47], v[180:183], v[64:67], v[32:47]
	v_mfma_f32_16x16x32_bf16 v[148:151], v[156:159], v[64:67], v[148:151]
	v_exp_f32_e32 v76, v76
	v_exp_f32_e32 v77, v77
	v_exp_f32_e32 v78, v78
	v_exp_f32_e32 v79, v79
	v_cvt_pk_bf16_f32 v70, v76, v77
	v_cvt_pk_bf16_f32 v71, v78, v79
	s_waitcnt lgkmcnt(0)
	s_nop 0
	v_mfma_f32_32x32x16_bf16 v[48:63], v[184:187], v[68:71], v[48:63]
	v_exp_f32_e32 v80, v80
	v_exp_f32_e32 v81, v81
	v_exp_f32_e32 v82, v82
	v_exp_f32_e32 v83, v83
	v_cvt_pk_bf16_f32 v80, v80, v81
	v_cvt_pk_bf16_f32 v81, v82, v83
	v_mfma_f32_32x32x16_bf16 v[32:47], v[204:207], v[68:71], v[32:47]
	v_mfma_f32_16x16x32_bf16 v[148:151], v[156:159], v[68:71], v[148:151]
	v_exp_f32_e32 v84, v84
	v_exp_f32_e32 v85, v85
	v_exp_f32_e32 v86, v86
	v_exp_f32_e32 v87, v87
	v_cvt_pk_bf16_f32 v82, v84, v85
	v_cvt_pk_bf16_f32 v83, v86, v87
	v_exp_f32_e32 v88, v88
	v_exp_f32_e32 v89, v89
	v_exp_f32_e32 v90, v90
	v_exp_f32_e32 v91, v91
	v_cvt_pk_bf16_f32 v84, v88, v89
	v_cvt_pk_bf16_f32 v85, v90, v91
	v_mfma_f32_32x32x16_bf16 v[16:31], v[228:231], v[80:83], v[16:31]
	v_exp_f32_e32 v92, v92
	v_exp_f32_e32 v93, v93
	v_exp_f32_e32 v94, v94
	v_exp_f32_e32 v95, v95
	v_cvt_pk_bf16_f32 v86, v92, v93
	v_cvt_pk_bf16_f32 v87, v94, v95
	v_mfma_f32_32x32x16_bf16 v[0:15], v[180:183], v[80:83], v[0:15]
	v_mfma_f32_16x16x32_bf16 v[152:155], v[156:159], v[80:83], v[152:155]
	v_mfma_f32_32x32x16_bf16 v[16:31], v[184:187], v[84:87], v[16:31]
	v_mfma_f32_32x32x16_bf16 v[0:15], v[204:207], v[84:87], v[0:15]
	v_mfma_f32_16x16x32_bf16 v[152:155], v[156:159], v[84:87], v[152:155]
	ds_read_b128 v[180:183], v128 offset:8192
	ds_read_b128 v[184:187], v130 offset:8192
	ds_read_b128 v[204:207], v128 offset:12288
	ds_read_b128 v[208:211], v130 offset:12288
	ds_read_b128 v[212:215], v131 offset:24576
	ds_read_b128 v[216:219], v131 offset:28672
	ds_read_b128 v[220:223], v188 offset:24576
	ds_read_b128 v[224:227], v188 offset:28672
	ds_read_b128 v[228:231], v189 offset:24576
	s_waitcnt lgkmcnt(7)
; #define MFMA32(a, b, c) __builtin_amdgcn_mfma_f32_32x32x16_bf16((a), (b), (c), 0, 0, 0)
; DI float fadd1(float a, float b) { float r; asm("v_add_f32 %0, %1, %2" : "=v"(r) : "v"(a), "v"(b)); return r; }
; template <int NKS>
; DI void attn_tile(const Params& p, int layer, int seq, int slot, int qt, char* smem, bool wr = true) {
;     ...
;       auto kb_body = [&](int kb) {
;         bf16x8 kf[NKS];
; #pragma unroll
;         for (int ks = 0; ks < NKS; ++ks) kf[ks] = *(const bf16x8*)(sK + swz(32 * kb + r, 2 * (ks0 + ks) + h));
;         bf16x8 pk[2][2];
; #pragma unroll
;         for (int qb = 0; qb < 2; ++qb) {
;           f32x16 st;
; #pragma unroll
;           for (int i = 0; i < 16; ++i) st[i] = SUB ? ncb[qb] : 0.f;
; #pragma unroll
;           for (int ks = 0; ks < NKS; ++ks) st = MFMA32(kf[ks], qf[qb][ks], st);
;           if constexpr (SUB) {
;             float ls = 0.f;
; #pragma unroll
;             for (int i = 0; i < 16; ++i) { float e = __builtin_amdgcn_exp2f(st[i]); st[i] = e; ls = fadd1(ls, e); }
;             lsum[qb] += ls;
;             pk[qb][0] = pack8(st, 0); pk[qb][1] = pack8(st, 1);
;           } else {
; #pragma unroll
;             for (int i = 0; i < 16; ++i) st[i] = __builtin_amdgcn_exp2f(st[i]);
;             pk[qb][0] = pack8(st, 0); pk[qb][1] = pack8(st, 1);
;             ls4[qb] = __builtin_amdgcn_mfma_f32_16x16x32_bf16(selA, pk[qb][0], ls4[qb], 0, 0, 0);
;             ls4[qb] = __builtin_amdgcn_mfma_f32_16x16x32_bf16(selA, pk[qb][1], ls4[qb], 0, 0, 0);
;           }
;         }
; #pragma unroll
;         for (int eb = 0; eb < 2; ++eb)
; #pragma unroll
;           for (int s2 = 0; s2 < 2; ++s2) {
;             bf16x8 vf = *(const bf16x8*)(sV + swz(32 * eb + r, 4 * kb + 2 * s2 + h));
; #pragma unroll
;             for (int qb = 0; qb < 2; ++qb) O[qb][eb] = MFMA32(vf, pk[qb][s2], O[qb][eb]);
;           }
;       };
;       if constexpr (SUB) {
; #pragma unroll 1
;         for (int kb = 0; kb < 2; ++kb) kb_body(kb);
;       } else {
;         kb_body(0); kb_body(1);
;       }
;       }
;     }
	v_mfma_f32_32x32x16_bf16 v[112:127], v[180:183], v[132:135], 0
	v_mfma_f32_32x32x16_bf16 v[112:127], v[184:187], v[136:139], v[112:127]
	v_mfma_f32_32x32x16_bf16 v[96:111], v[180:183], v[140:143], 0
	v_mfma_f32_32x32x16_bf16 v[96:111], v[184:187], v[144:147], v[96:111]
	ds_read_b128 v[180:183], v189 offset:28672
	ds_read_b128 v[184:187], v190 offset:24576
	s_waitcnt lgkmcnt(7)
	v_mfma_f32_32x32x16_bf16 v[64:79], v[204:207], v[132:135], 0
	v_mfma_f32_32x32x16_bf16 v[64:79], v[208:211], v[136:139], v[64:79]
	s_nop 4
	v_exp_f32_e32 v112, v112
	v_exp_f32_e32 v113, v113
	v_exp_f32_e32 v114, v114
	v_exp_f32_e32 v115, v115
	v_cvt_pk_bf16_f32 v112, v112, v113
	v_cvt_pk_bf16_f32 v113, v114, v115
	v_mfma_f32_32x32x16_bf16 v[80:95], v[204:207], v[140:143], 0
	ds_read_b128 v[204:207], v190 offset:28672
	v_exp_f32_e32 v116, v116
	v_exp_f32_e32 v117, v117
	v_exp_f32_e32 v118, v118
	v_exp_f32_e32 v119, v119
	v_cvt_pk_bf16_f32 v114, v116, v117
	v_cvt_pk_bf16_f32 v115, v118, v119
	v_mfma_f32_32x32x16_bf16 v[80:95], v[208:211], v[144:147], v[80:95]
	v_exp_f32_e32 v120, v120
	v_exp_f32_e32 v121, v121
	v_exp_f32_e32 v122, v122
	v_exp_f32_e32 v123, v123
	v_cvt_pk_bf16_f32 v116, v120, v121
	v_cvt_pk_bf16_f32 v117, v122, v123
	s_waitcnt lgkmcnt(6)
	v_mfma_f32_32x32x16_bf16 v[48:63], v[212:215], v[112:115], v[48:63]
	v_exp_f32_e32 v124, v124
	v_exp_f32_e32 v125, v125
	v_exp_f32_e32 v126, v126
	v_exp_f32_e32 v127, v127
	v_cvt_pk_bf16_f32 v118, v124, v125
	v_cvt_pk_bf16_f32 v119, v126, v127
	v_mfma_f32_32x32x16_bf16 v[32:47], v[216:219], v[112:115], v[32:47]
	v_exp_f32_e32 v96, v96
	v_exp_f32_e32 v97, v97
	v_exp_f32_e32 v98, v98
	v_exp_f32_e32 v99, v99
	v_cvt_pk_bf16_f32 v96, v96, v97
	v_cvt_pk_bf16_f32 v97, v98, v99
	v_mfma_f32_16x16x32_bf16 v[148:151], v[156:159], v[112:115], v[148:151]
	s_waitcnt lgkmcnt(4)
	v_mfma_f32_32x32x16_bf16 v[48:63], v[220:223], v[116:119], v[48:63]
	v_exp_f32_e32 v100, v100
	v_exp_f32_e32 v101, v101
	v_exp_f32_e32 v102, v102
	v_exp_f32_e32 v103, v103
	v_cvt_pk_bf16_f32 v98, v100, v101
	v_cvt_pk_bf16_f32 v99, v102, v103
	v_mfma_f32_32x32x16_bf16 v[32:47], v[224:227], v[116:119], v[32:47]
	v_mfma_f32_16x16x32_bf16 v[148:151], v[156:159], v[116:119], v[148:151]
	v_exp_f32_e32 v104, v104
	v_exp_f32_e32 v105, v105
	v_exp_f32_e32 v106, v106
	v_exp_f32_e32 v107, v107
	v_cvt_pk_bf16_f32 v100, v104, v105
	v_cvt_pk_bf16_f32 v101, v106, v107
	v_mfma_f32_32x32x16_bf16 v[16:31], v[212:215], v[96:99], v[16:31]
	v_exp_f32_e32 v108, v108
	v_exp_f32_e32 v109, v109
	v_exp_f32_e32 v110, v110
	v_exp_f32_e32 v111, v111
	v_cvt_pk_bf16_f32 v102, v108, v109
	v_cvt_pk_bf16_f32 v103, v110, v111
	v_mfma_f32_32x32x16_bf16 v[0:15], v[216:219], v[96:99], v[0:15]
	v_mfma_f32_16x16x32_bf16 v[152:155], v[156:159], v[96:99], v[152:155]
	v_exp_f32_e32 v64, v64
	v_exp_f32_e32 v65, v65
	v_exp_f32_e32 v66, v66
	v_exp_f32_e32 v67, v67
	v_cvt_pk_bf16_f32 v64, v64, v65
	v_cvt_pk_bf16_f32 v65, v66, v67
	v_mfma_f32_32x32x16_bf16 v[16:31], v[220:223], v[100:103], v[16:31]
	v_mfma_f32_32x32x16_bf16 v[0:15], v[224:227], v[100:103], v[0:15]
	v_exp_f32_e32 v68, v68
	v_exp_f32_e32 v69, v69
	v_exp_f32_e32 v70, v70
	v_exp_f32_e32 v71, v71
	v_cvt_pk_bf16_f32 v66, v68, v69
	v_cvt_pk_bf16_f32 v67, v70, v71
	v_mfma_f32_16x16x32_bf16 v[152:155], v[156:159], v[100:103], v[152:155]
	s_waitcnt lgkmcnt(2)
	v_mfma_f32_32x32x16_bf16 v[48:63], v[228:231], v[64:67], v[48:63]
	v_exp_f32_e32 v72, v72
	v_exp_f32_e32 v73, v73
	v_exp_f32_e32 v74, v74
	v_exp_f32_e32 v75, v75
	v_cvt_pk_bf16_f32 v68, v72, v73
	v_cvt_pk_bf16_f32 v69, v74, v75
	v_mfma_f32_32x32x16_bf16 v[32:47], v[180:183], v[64:67], v[32:47]
	v_mfma_f32_16x16x32_bf16 v[148:151], v[156:159], v[64:67], v[148:151]
	v_exp_f32_e32 v76, v76
	v_exp_f32_e32 v77, v77
	v_exp_f32_e32 v78, v78
	v_exp_f32_e32 v79, v79
	v_cvt_pk_bf16_f32 v70, v76, v77
	v_cvt_pk_bf16_f32 v71, v78, v79
	s_waitcnt lgkmcnt(0)
	s_nop 0
	v_mfma_f32_32x32x16_bf16 v[48:63], v[184:187], v[68:71], v[48:63]
	v_exp_f32_e32 v80, v80
	v_exp_f32_e32 v81, v81
	v_exp_f32_e32 v82, v82
	v_exp_f32_e32 v83, v83
	v_cvt_pk_bf16_f32 v80, v80, v81
	v_cvt_pk_bf16_f32 v81, v82, v83
	v_mfma_f32_32x32x16_bf16 v[32:47], v[204:207], v[68:71], v[32:47]
	v_mfma_f32_16x16x32_bf16 v[148:151], v[156:159], v[68:71], v[148:151]
	v_exp_f32_e32 v84, v84
	v_exp_f32_e32 v85, v85
	v_exp_f32_e32 v86, v86
	v_exp_f32_e32 v87, v87
	v_cvt_pk_bf16_f32 v82, v84, v85
	v_cvt_pk_bf16_f32 v83, v86, v87
	v_exp_f32_e32 v88, v88
	v_exp_f32_e32 v89, v89
	v_exp_f32_e32 v90, v90
	v_exp_f32_e32 v91, v91
	v_cvt_pk_bf16_f32 v84, v88, v89
	v_cvt_pk_bf16_f32 v85, v90, v91
	v_mfma_f32_32x32x16_bf16 v[16:31], v[228:231], v[80:83], v[16:31]
	v_exp_f32_e32 v92, v92
	v_exp_f32_e32 v93, v93
	v_exp_f32_e32 v94, v94
	v_exp_f32_e32 v95, v95
	v_cvt_pk_bf16_f32 v86, v92, v93
	v_cvt_pk_bf16_f32 v87, v94, v95
	v_mfma_f32_32x32x16_bf16 v[0:15], v[180:183], v[80:83], v[0:15]
	v_mfma_f32_16x16x32_bf16 v[152:155], v[156:159], v[80:83], v[152:155]
	v_mfma_f32_32x32x16_bf16 v[16:31], v[184:187], v[84:87], v[16:31]
	v_mfma_f32_32x32x16_bf16 v[0:15], v[204:207], v[84:87], v[0:15]
	v_mfma_f32_16x16x32_bf16 v[152:155], v[156:159], v[84:87], v[152:155]
	s_cmp_eq_u32 s36, s31
	s_cbranch_scc1 .LBB0_1420
	s_mov_b32 s37, s36
	s_branch .LBB0_1414
